# non-temporal hint extended to every 16-byte and 8-byte global store (all streamed intermediates and outputs), on top of v22
# baseline (speedup 1.0000x reference)
; DI unsigned pk2(float lo, float hi) { unsigned r; asm volatile("v_cvt_pk_bf16_f32 %0, %1, %2" : "=v"(r) : "v"(lo), "v"(hi)); return r; }
; DI float bflo(unsigned u) { return __uint_as_float(u << 16); }
; DI float bfhi(unsigned u) { return __uint_as_float(u & 0xffff0000u); }
; DI void phase_prologue(const Prm& p, LAS unsigned char* lds, int tid, int lane, int wave) {
;     ...
;     for (int row = gw; row < NT; row += NGW) {
;         const float* src;
;         if (row < NTP) { const int b = row / TP, t = row - b * TP; src = t < 16 ? p.meta + (size_t)t * 1024 : p.x_prompt + ((size_t)b * 4096 + (t - 16)) * 1024; }
;         else src = p.x_sample + (size_t)(row - NTP) * 1024;
;         float ss = 0.f;
; #pragma unroll
;         for (int j = 0; j < 4; ++j) { const f32x4 v = ((const f32x4*)src)[lane + 64 * j]; u32x2 o; o.x = pk2(v.x, v.y); o.y = pk2(v.z, v.w);
;             const float a0 = bflo(o.x), a1 = bfhi(o.x), a2 = bflo(o.y), a3 = bfhi(o.y); ss += (a0 * a0 + a1 * a1) + (a2 * a2 + a3 * a3);
;             ((u32x2*)(p.XB + (size_t)row * 1024))[lane + 64 * j] = o; }
;         ss = wave_sum(ss);
;         if (lane < 16) p.SSQ[(size_t)row * 16 + lane] = lane == 0 ? ss : 0.f;
;         if (lane == 0) p.RINV[row] = rsqrtf(ss * (1.f / 1024.f) + EPSN);
;     }
.Lrw_compute:
	v_cvt_pk_bf16_f32 v134, v102, v103
	v_cvt_pk_bf16_f32 v135, v104, v105
	global_store_dwordx2 v[6:7], v[134:135], off offset:-1024 nt
	v_lshlrev_b32_e32 v193, 16, v134
	v_and_b32_e32 v194, 0xffff0000, v134
	v_lshlrev_b32_e32 v195, 16, v135
	v_and_b32_e32 v196, 0xffff0000, v135
	v_mul_f32_e32 v194, v194, v194
	v_mul_f32_e32 v196, v196, v196
	v_fmac_f32_e32 v194, v193, v193
	v_fmac_f32_e32 v196, v195, v195
	v_add_f32_e32 v142, v194, v196
	v_cvt_pk_bf16_f32 v136, v106, v107
	v_cvt_pk_bf16_f32 v137, v108, v109
	global_store_dwordx2 v[6:7], v[136:137], off offset:-512 nt
	v_lshlrev_b32_e32 v193, 16, v136
	v_and_b32_e32 v194, 0xffff0000, v136
	v_lshlrev_b32_e32 v195, 16, v137
	v_and_b32_e32 v196, 0xffff0000, v137
	v_mul_f32_e32 v194, v194, v194
	v_mul_f32_e32 v196, v196, v196
	v_fmac_f32_e32 v194, v193, v193
	v_fmac_f32_e32 v196, v195, v195
	v_add_f32_e32 v143, v194, v196
	v_cvt_pk_bf16_f32 v138, v110, v111
	v_cvt_pk_bf16_f32 v139, v112, v113
	global_store_dwordx2 v[6:7], v[138:139], off nt
	v_lshlrev_b32_e32 v193, 16, v138
	v_and_b32_e32 v194, 0xffff0000, v138
	v_lshlrev_b32_e32 v195, 16, v139
	v_and_b32_e32 v196, 0xffff0000, v139
	v_mul_f32_e32 v194, v194, v194
	v_mul_f32_e32 v196, v196, v196
	v_fmac_f32_e32 v194, v193, v193
	v_fmac_f32_e32 v196, v195, v195
	v_add_f32_e32 v144, v194, v196
	v_cvt_pk_bf16_f32 v140, v114, v115
	v_cvt_pk_bf16_f32 v141, v116, v117
	global_store_dwordx2 v[6:7], v[140:141], off offset:512 nt
	v_lshlrev_b32_e32 v193, 16, v140
	v_and_b32_e32 v194, 0xffff0000, v140
	v_lshlrev_b32_e32 v195, 16, v141
	v_and_b32_e32 v196, 0xffff0000, v141
	v_mul_f32_e32 v194, v194, v194
	v_mul_f32_e32 v196, v196, v196
	v_fmac_f32_e32 v194, v193, v193
	v_fmac_f32_e32 v196, v195, v195
	v_add_f32_e32 v192, v194, v196
	v_add_f32_e32 v142, v142, v143
	v_add_f32_e32 v142, v142, v144
	v_add_f32_e32 v20, v142, v192
	v_cmp_lt_i32_e32 vcc, v10, v9
	s_nop 1
	v_cndmask_b32_e32 v21, v8, v10, vcc
	v_lshlrev_b32_e32 v21, 2, v21
	ds_bpermute_b32 v17, v21, v20
	s_waitcnt lgkmcnt(0)
	v_add_f32_e32 v20, v20, v17
	v_cmp_lt_i32_e32 vcc, v11, v9
	s_nop 1
	v_cndmask_b32_e32 v21, v8, v11, vcc
	v_lshlrev_b32_e32 v21, 2, v21
	ds_bpermute_b32 v17, v21, v20
	s_waitcnt lgkmcnt(0)
	v_add_f32_e32 v20, v20, v17
	v_cmp_lt_i32_e32 vcc, v12, v9
	s_nop 1
	v_cndmask_b32_e32 v21, v8, v12, vcc
	v_lshlrev_b32_e32 v21, 2, v21
	ds_bpermute_b32 v17, v21, v20
	s_waitcnt lgkmcnt(0)
	v_add_f32_e32 v20, v20, v17
	v_cmp_lt_i32_e32 vcc, v13, v9
	s_nop 1
	v_cndmask_b32_e32 v21, v8, v13, vcc
	v_lshlrev_b32_e32 v21, 2, v21
	ds_bpermute_b32 v17, v21, v20
	s_waitcnt lgkmcnt(0)
	v_add_f32_e32 v20, v20, v17
	v_cmp_lt_i32_e32 vcc, v14, v9
	s_nop 1
	v_cndmask_b32_e32 v21, v8, v14, vcc
	v_lshlrev_b32_e32 v21, 2, v21
	ds_bpermute_b32 v17, v21, v20
	s_waitcnt lgkmcnt(0)
	v_add_f32_e32 v20, v20, v17
	v_cmp_lt_i32_e32 vcc, v15, v9
	s_nop 1
	v_cndmask_b32_e32 v21, v8, v15, vcc
	v_lshlrev_b32_e32 v21, 2, v21
	ds_bpermute_b32 v17, v21, v20
	s_waitcnt lgkmcnt(0)
	v_add_f32_e32 v20, v20, v17
	v_mov_b32_e32 v17, v20
	s_mov_b64 s[44:45], exec
	s_and_b64 exec, s[44:45], s[2:3]
	v_cndmask_b32_e64 v18, 0, v17, s[4:5]
	global_store_dword v[4:5], v18, off
	s_mov_b64 exec, s[44:45]
	v_fmamk_f32 v17, v17, 0x3a800000, v16
	s_mov_b32 s40, 0x800000
	v_cmp_gt_f32_e32 vcc, s40, v17
	v_mul_f32_e32 v18, 0x4b800000, v17
	s_nop 1
	v_cndmask_b32_e32 v17, v17, v18, vcc
	v_rsq_f32_e32 v17, v17
	s_nop 0
	v_mul_f32_e32 v18, 0x45800000, v17
	v_cndmask_b32_e32 v17, v17, v18, vcc
	s_and_b64 exec, s[44:45], s[4:5]
	global_store_dword v3, v17, s[24:25]
	s_mov_b64 exec, s[44:45]
	s_add_u32 s24, s24, s26
	s_addc_u32 s25, s25, s27
	v_lshl_add_u64 v[4:5], v[4:5], 0, s[36:37]
	v_lshl_add_u64 v[6:7], v[6:7], 0, s[38:39]
	s_mov_b32 s8, s56
	s_add_i32 s6, s8, 0x8080
	s_cmp_gt_i32 s6, 0x827f
	s_cbranch_scc1 .Lrw_done
	s_waitcnt vmcnt(6)
	v_mov_b64_e32 v[102:103], v[118:119]
	v_mov_b64_e32 v[104:105], v[120:121]
	v_mov_b64_e32 v[106:107], v[122:123]
	v_mov_b64_e32 v[108:109], v[124:125]
	v_mov_b64_e32 v[110:111], v[126:127]
	v_mov_b64_e32 v[112:113], v[128:129]
	v_mov_b64_e32 v[114:115], v[130:131]
	v_mov_b64_e32 v[116:117], v[132:133]
	s_branch .Lrw_loop

; DI void s5_pow(const Prm& p, int g, int n, float k, float& re, float& im) {
;     const float dt = __expf(p.log_dt[g]), ar = p.a_re[g * 64 + n], ai = p.a_im[g * 64 + n];
;     const float mag = __expf(k * dt * ar); float rev = k * dt * ai * 0.15915494309189535f; rev -= rintf(rev);
;     re = mag * __builtin_amdgcn_cosf(rev); im = mag * __builtin_amdgcn_sinf(rev);
; }
; DI void phase_prologue(const Prm& p, LAS unsigned char* lds, int tid, int lane, int wave) {
;     ...
;     if (gtid < 2048) { float wr_, wi_; s5_pow(p, gtid >> 6, gtid & 63, 16.f, wr_, wi_); p.A16[2 * gtid] = wr_; p.A16[2 * gtid + 1] = wi_; }
.LBB0_110:
	v_writelane_b32 v255, s8, 6
	s_nop 1
	v_writelane_b32 v255, s9, 7
	s_or_b64 exec, exec, s[4:5]
	s_load_dwordx16 s[16:31], s[0:1], 0x198
	s_movk_i32 s0, 0x800
	v_cmp_gt_i32_e32 vcc, s0, v162
	s_waitcnt lgkmcnt(0)
	v_writelane_b32 v255, s16, 8
	s_nop 1
	v_writelane_b32 v255, s17, 9
	v_writelane_b32 v255, s18, 10
	v_writelane_b32 v255, s19, 11
	v_writelane_b32 v255, s20, 12
	v_writelane_b32 v255, s21, 13
	v_writelane_b32 v255, s22, 14
	v_writelane_b32 v255, s23, 15
	v_writelane_b32 v255, s24, 16
	v_writelane_b32 v255, s25, 17
	v_writelane_b32 v255, s26, 18
	v_writelane_b32 v255, s27, 19
	v_writelane_b32 v255, s28, 20
	v_writelane_b32 v255, s29, 21
	v_writelane_b32 v255, s30, 22
	v_writelane_b32 v255, s31, 23
	s_and_saveexec_b64 s[0:1], vcc
	s_cbranch_execz .LBB0_112
	v_ashrrev_i32_e32 v2, 6, v162
	v_ashrrev_i32_e32 v3, 31, v2
	v_lshl_add_u64 v[2:3], v[2:3], 2, s[12:13]
	global_load_dword v1, v[2:3], off
	v_lshlrev_b64 v[2:3], 2, v[162:163]
	v_lshl_add_u64 v[4:5], s[80:81], 0, v[2:3]
	v_lshl_add_u64 v[2:3], s[82:83], 0, v[2:3]
	global_load_dword v4, v[4:5], off
	s_nop 0
	global_load_dword v2, v[2:3], off
	v_lshlrev_b32_e32 v6, 1, v162
	v_ashrrev_i32_e32 v7, 31, v6
	v_lshl_add_u64 v[6:7], v[6:7], 2, s[40:41]
	s_waitcnt vmcnt(2)
	v_mul_f32_e32 v1, 0x3fb8aa3b, v1
	v_exp_f32_e32 v1, v1
	s_nop 0
	v_mul_f32_e32 v1, 0x41800000, v1
	s_waitcnt vmcnt(1)
	v_mul_f32_e32 v3, v4, v1
	s_waitcnt vmcnt(0)
	v_mul_f32_e32 v1, v2, v1
	v_mul_f32_e32 v2, 0x3fb8aa3b, v3
	v_mul_f32_e32 v3, 0.15915494, v1
	v_rndne_f32_e32 v3, v3
	v_fma_f32 v1, v1, 0.15915494, -v3
	v_exp_f32_e32 v2, v2
	v_cos_f32_e32 v4, v1
	v_sin_f32_e32 v5, v1
	s_nop 0
	v_pk_mul_f32 v[2:3], v[2:3], v[4:5] op_sel_hi:[0,1]
	global_store_dwordx2 v[6:7], v[2:3], off nt

; #define LAS __attribute__((address_space(3)))
; DI unsigned pk2(float lo, float hi) { unsigned r; asm volatile("v_cvt_pk_bf16_f32 %0, %1, %2" : "=v"(r) : "v"(lo), "v"(hi)); return r; }
; #define MFMA16(a, b, c) __builtin_amdgcn_mfma_f32_16x16x32_bf16((a), (b), (c), 0, 0, 0)
; DI void hgrn_b1_all(const Prm& p, LAS unsigned char* lds, int tid, int lane, int wave) {
;     ...
;         const LAS float* vec = (const LAS float*)(lds + L_VEC);
;         bf16x8 a[2];
; #pragma unroll
;         for (int ks = 0; ks < 2; ++ks) a[ks] = *(const LAS bf16x8*)(lds + L_KTT + ((16 * wave + fr) * TPI + 32 * ks + 8 * fq) * 2);
;         float e2[4];
; #pragma unroll
;         for (int j = 0; j < 4; ++j) { const int d = 16 * wave + 4 * fq + j; e2[j] = __expf(vec[128 + d] - vec[d]); }
; #pragma unroll
;         for (int vt = 0; vt < 8; ++vt) { f32x4 acc = {0.f, 0.f, 0.f, 0.f};
; #pragma unroll
;             for (int ks = 0; ks < 2; ++ks) { const bf16x8 b = *(const LAS bf16x8*)(lds + L_IVT + ((16 * vt + fr) * TPI + 32 * ks + 8 * fq) * 2); acc = MFMA16(a[ks], b, acc); }
;             u32x2 o; o.x = pk2(acc[0] * e2[0], acc[1] * e2[1]); o.y = pk2(acc[2] * e2[2], acc[3] * e2[3]);
;             *(u32x2*)(p.UT + (size_t)item * 16384 + (16 * vt + fr) * 128 + 16 * wave + 4 * fq) = o; }
;         if (tid < 128) p.AL[(size_t)item * 128 + tid] = __expf(vec[128 + tid]);
.LBB0_769:
	v_add_u32_e32 v46, s20, v87
	ds_read_b128 v[36:39], v89 offset:52224
	ds_read_b128 v[32:35], v89 offset:52288
	ds_read_b128 v[94:97], v46 offset:512
	ds_read_b128 v[98:101], v46
	s_ashr_i32 s11, s10, 31
	s_lshl_b64 s[14:15], s[10:11], 15
	s_waitcnt lgkmcnt(0)
	v_sub_f32_e32 v46, v94, v98
	v_mul_f32_e32 v46, 0x3fb8aa3b, v46
	v_exp_f32_e32 v104, v46
	v_sub_f32_e32 v46, v95, v99
	v_mul_f32_e32 v46, 0x3fb8aa3b, v46
	v_exp_f32_e32 v105, v46
	v_sub_f32_e32 v46, v96, v100
	v_mul_f32_e32 v46, 0x3fb8aa3b, v46
	v_exp_f32_e32 v106, v46
	v_sub_f32_e32 v46, v97, v101
	ds_read_b128 v[94:97], v90
	ds_read_b128 v[98:101], v90 offset:64
	s_waitcnt lgkmcnt(1)
	v_mfma_f32_16x16x32_bf16 v[94:97], v[36:39], v[94:97], 0
	v_mul_f32_e32 v46, 0x3fb8aa3b, v46
	v_exp_f32_e32 v107, v46
	s_waitcnt lgkmcnt(0)
	v_mfma_f32_16x16x32_bf16 v[94:97], v[32:35], v[98:101], v[94:97]
	s_nop 7
	v_mul_f32_e32 v46, v104, v94
	v_mul_f32_e32 v47, v105, v95
	v_cvt_pk_bf16_f32 v94, v46, v47
	v_mul_f32_e32 v46, v106, v96
	v_mul_f32_e32 v47, v107, v97
	v_cvt_pk_bf16_f32 v95, v46, v47
	v_lshl_add_u64 v[46:47], v[42:43], 0, s[14:15]
	v_lshl_add_u64 v[46:47], v[46:47], 0, s[6:7]
	v_lshl_add_u64 v[46:47], v[46:47], 0, v[40:41]
	global_store_dwordx2 v[46:47], v[94:95], off nt
	ds_read_b128 v[94:97], v90 offset:2304
	ds_read_b128 v[98:101], v90 offset:2368
	s_waitcnt lgkmcnt(1)
	v_mfma_f32_16x16x32_bf16 v[94:97], v[36:39], v[94:97], 0
	s_movk_i32 s14, 0x2000
	v_add_co_u32_e32 v102, vcc, s14, v46
	s_waitcnt lgkmcnt(0)
	v_mfma_f32_16x16x32_bf16 v[94:97], v[32:35], v[98:101], v[94:97]
	v_addc_co_u32_e32 v103, vcc, 0, v47, vcc
	s_movk_i32 s14, 0x4000
	s_nop 5
	v_mul_f32_e32 v94, v104, v94
	v_mul_f32_e32 v95, v105, v95
	v_cvt_pk_bf16_f32 v94, v94, v95
	v_mul_f32_e32 v95, v106, v96
	v_mul_f32_e32 v96, v107, v97
	v_cvt_pk_bf16_f32 v95, v95, v96
	global_store_dwordx2 v[102:103], v[94:95], off offset:-4096 nt
	ds_read_b128 v[94:97], v90 offset:4608
	ds_read_b128 v[98:101], v90 offset:4672
	s_waitcnt lgkmcnt(1)
	v_mfma_f32_16x16x32_bf16 v[94:97], v[36:39], v[94:97], 0
	s_waitcnt lgkmcnt(0)
	v_mfma_f32_16x16x32_bf16 v[94:97], v[32:35], v[98:101], v[94:97]
	s_nop 7
	v_mul_f32_e32 v94, v104, v94
	v_mul_f32_e32 v95, v105, v95
	v_cvt_pk_bf16_f32 v94, v94, v95
	v_mul_f32_e32 v95, v106, v96
	v_mul_f32_e32 v96, v107, v97
	v_cvt_pk_bf16_f32 v95, v95, v96
	global_store_dwordx2 v[102:103], v[94:95], off nt
	ds_read_b128 v[94:97], v91
	ds_read_b128 v[98:101], v91 offset:64
	s_waitcnt lgkmcnt(1)
	v_mfma_f32_16x16x32_bf16 v[94:97], v[36:39], v[94:97], 0
	v_add_co_u32_e32 v102, vcc, s14, v46
	s_movk_i32 s14, 0x6000
	s_waitcnt lgkmcnt(0)
	v_mfma_f32_16x16x32_bf16 v[94:97], v[32:35], v[98:101], v[94:97]
	v_addc_co_u32_e32 v103, vcc, 0, v47, vcc
	s_nop 6
	v_mul_f32_e32 v94, v104, v94
	v_mul_f32_e32 v95, v105, v95
	v_cvt_pk_bf16_f32 v94, v94, v95
	v_mul_f32_e32 v95, v106, v96
	v_mul_f32_e32 v96, v107, v97
	v_cvt_pk_bf16_f32 v95, v95, v96
	global_store_dwordx2 v[102:103], v[94:95], off offset:-4096 nt
	ds_read_b128 v[94:97], v90 offset:9216
	ds_read_b128 v[98:101], v90 offset:9280
	s_waitcnt lgkmcnt(1)
	v_mfma_f32_16x16x32_bf16 v[94:97], v[36:39], v[94:97], 0
	s_waitcnt lgkmcnt(0)
	v_mfma_f32_16x16x32_bf16 v[94:97], v[32:35], v[98:101], v[94:97]
	s_nop 7
	v_mul_f32_e32 v94, v104, v94
	v_mul_f32_e32 v95, v105, v95
	v_cvt_pk_bf16_f32 v94, v94, v95
	v_mul_f32_e32 v95, v106, v96
	v_mul_f32_e32 v96, v107, v97
	v_cvt_pk_bf16_f32 v95, v95, v96
	global_store_dwordx2 v[102:103], v[94:95], off nt
	ds_read_b128 v[94:97], v90 offset:11520
	ds_read_b128 v[98:101], v90 offset:11584
	s_waitcnt lgkmcnt(1)
	v_mfma_f32_16x16x32_bf16 v[94:97], v[36:39], v[94:97], 0
	v_add_co_u32_e32 v102, vcc, s14, v46
	s_waitcnt lgkmcnt(0)
	v_mfma_f32_16x16x32_bf16 v[94:97], v[32:35], v[98:101], v[94:97]
	v_addc_co_u32_e32 v103, vcc, 0, v47, vcc
	s_nop 6
	v_mul_f32_e32 v94, v104, v94
	v_mul_f32_e32 v95, v105, v95
	v_cvt_pk_bf16_f32 v94, v94, v95
	v_mul_f32_e32 v95, v106, v96
	v_mul_f32_e32 v96, v107, v97
	v_cvt_pk_bf16_f32 v95, v95, v96
	global_store_dwordx2 v[102:103], v[94:95], off offset:-4096 nt
	ds_read_b128 v[94:97], v90 offset:13824
	ds_read_b128 v[98:101], v90 offset:13888
	s_waitcnt lgkmcnt(1)
	v_mfma_f32_16x16x32_bf16 v[94:97], v[36:39], v[94:97], 0
	s_waitcnt lgkmcnt(0)
	v_mfma_f32_16x16x32_bf16 v[94:97], v[32:35], v[98:101], v[94:97]
	s_nop 7
	v_mul_f32_e32 v94, v104, v94
	v_mul_f32_e32 v95, v105, v95
	v_cvt_pk_bf16_f32 v94, v94, v95
	v_mul_f32_e32 v95, v106, v96
	v_mul_f32_e32 v96, v107, v97
	v_cvt_pk_bf16_f32 v95, v95, v96
	global_store_dwordx2 v[102:103], v[94:95], off nt
	ds_read_b128 v[94:97], v92
	s_waitcnt lgkmcnt(0)
	v_mfma_f32_16x16x32_bf16 v[36:39], v[36:39], v[94:97], 0
	ds_read_b128 v[94:97], v92 offset:64
	s_waitcnt lgkmcnt(0)
	v_mfma_f32_16x16x32_bf16 v[32:35], v[32:35], v[94:97], v[36:39]
	s_nop 7
	v_mul_f32_e32 v32, v104, v32
	v_mul_f32_e32 v33, v105, v33
	v_cvt_pk_bf16_f32 v32, v32, v33
	v_mul_f32_e32 v33, v106, v34
	v_mul_f32_e32 v34, v107, v35
	v_cvt_pk_bf16_f32 v33, v33, v34
	v_add_co_u32_e32 v34, vcc, 0x7000, v46
	s_nop 1
	v_addc_co_u32_e32 v35, vcc, 0, v47, vcc
	global_store_dwordx2 v[34:35], v[32:33], off nt
	s_and_saveexec_b64 s[14:15], s[0:1]
	s_cbranch_execz .LBB0_652
	ds_read_b32 v32, v88 offset:512
	s_lshl_b64 s[10:11], s[10:11], 9
	s_waitcnt lgkmcnt(0)
	v_mul_f32_e32 v32, 0x3fb8aa3b, v32
	v_exp_f32_e32 v34, v32
	v_lshl_add_u64 v[32:33], v[44:45], 0, s[10:11]
	global_store_dword v[32:33], v34, off
	s_branch .LBB0_652

; DI unsigned pk2(float lo, float hi) { unsigned r; asm volatile("v_cvt_pk_bf16_f32 %0, %1, %2" : "=v"(r) : "v"(lo), "v"(hi)); return r; }
; DI float bflo(unsigned u) { return __uint_as_float(u << 16); }
; DI float bfhi(unsigned u) { return __uint_as_float(u & 0xffff0000u); }
; template <int NB> DI void hgrn_b2_steps(const Prm& p, int item, int v, int d4, float (&S)[4]) {
;     u32x2 uu[NB]; f32x4 al[NB];
; #pragma unroll
;     for (int i = 0; i < NB; ++i) { uu[i] = *(const u32x2*)(p.UT + (size_t)(item + i) * 16384 + v * 128 + d4); al[i] = *(const f32x4*)(p.AL + (size_t)(item + i) * 128 + d4); }
; #pragma unroll
;     for (int i = 0; i < NB; ++i) { u32x2 o; o.x = pk2(S[0], S[1]); o.y = pk2(S[2], S[3]);
;         *(u32x2*)(p.UT + (size_t)(item + i) * 16384 + v * 128 + d4) = o;
;         S[0] = al[i][0] * S[0] + bflo(uu[i].x); S[1] = al[i][1] * S[1] + bfhi(uu[i].x); S[2] = al[i][2] * S[2] + bflo(uu[i].y); S[3] = al[i][3] * S[3] + bfhi(uu[i].y); }
; }
; DI void hgrn_b2(const Prm& p, int gtid, int GT) {
;     ...
;         else { for (int c0 = 0; c0 < 65; c0 += 13) hgrn_b2_steps<13>(p, bhx * 65 + c0, v, d4, S); }
.LBB0_847:
	v_add_co_u32_e32 v80, vcc, 0x8000, v10
	global_load_dwordx2 v[78:79], v[10:11], off
	global_load_dwordx4 v[26:29], v[12:13], off offset:-512
	v_addc_co_u32_e32 v81, vcc, 0, v11, vcc
	v_add_u32_e32 v0, s15, v2
	global_load_dwordx2 v[82:83], v[80:81], off
	global_load_dwordx4 v[30:33], v[12:13], off
	v_add_u32_e32 v34, 15, v0
	v_ashrrev_i32_e32 v35, 31, v34
	v_add_u32_e32 v38, 16, v0
	v_lshlrev_b64 v[36:37], 15, v[34:35]
	v_ashrrev_i32_e32 v39, 31, v38
	v_add_u32_e32 v42, 17, v0
	v_lshl_add_u64 v[84:85], v[4:5], 0, v[36:37]
	v_lshlrev_b64 v[34:35], 9, v[34:35]
	v_lshlrev_b64 v[40:41], 15, v[38:39]
	v_ashrrev_i32_e32 v43, 31, v42
	global_load_dwordx2 v[86:87], v[84:85], off
	v_lshl_add_u64 v[34:35], v[6:7], 0, v[34:35]
	v_lshl_add_u64 v[88:89], v[4:5], 0, v[40:41]
	v_lshlrev_b64 v[38:39], 9, v[38:39]
	v_lshlrev_b64 v[44:45], 15, v[42:43]
	global_load_dwordx4 v[34:37], v[34:35], off
	v_lshl_add_u64 v[38:39], v[6:7], 0, v[38:39]
	global_load_dwordx2 v[90:91], v[88:89], off
	v_lshl_add_u64 v[92:93], v[4:5], 0, v[44:45]
	v_lshlrev_b64 v[42:43], 9, v[42:43]
	global_load_dwordx4 v[38:41], v[38:39], off
	v_lshl_add_u64 v[42:43], v[6:7], 0, v[42:43]
	global_load_dwordx2 v[94:95], v[92:93], off
	v_add_u32_e32 v46, 18, v0
	global_load_dwordx4 v[42:45], v[42:43], off
	v_ashrrev_i32_e32 v47, 31, v46
	v_lshlrev_b64 v[48:49], 15, v[46:47]
	v_add_u32_e32 v50, 19, v0
	v_lshl_add_u64 v[96:97], v[4:5], 0, v[48:49]
	v_lshlrev_b64 v[46:47], 9, v[46:47]
	v_ashrrev_i32_e32 v51, 31, v50
	v_add_u32_e32 v54, 20, v0
	global_load_dwordx2 v[98:99], v[96:97], off
	v_lshl_add_u64 v[46:47], v[6:7], 0, v[46:47]
	v_lshlrev_b64 v[52:53], 15, v[50:51]
	v_ashrrev_i32_e32 v55, 31, v54
	v_add_u32_e32 v58, 21, v0
	global_load_dwordx4 v[46:49], v[46:47], off
	v_lshl_add_u64 v[100:101], v[4:5], 0, v[52:53]
	v_lshlrev_b64 v[50:51], 9, v[50:51]
	v_lshlrev_b64 v[56:57], 15, v[54:55]
	v_ashrrev_i32_e32 v59, 31, v58
	v_add_u32_e32 v62, 22, v0
	global_load_dwordx2 v[102:103], v[100:101], off
	v_lshl_add_u64 v[50:51], v[6:7], 0, v[50:51]
	v_lshl_add_u64 v[106:107], v[4:5], 0, v[56:57]
	v_lshlrev_b64 v[54:55], 9, v[54:55]
	v_lshlrev_b64 v[60:61], 15, v[58:59]
	v_ashrrev_i32_e32 v63, 31, v62
	v_add_u32_e32 v66, 23, v0
	global_load_dwordx4 v[50:53], v[50:51], off
	v_lshl_add_u64 v[54:55], v[6:7], 0, v[54:55]
	global_load_dwordx2 v[108:109], v[106:107], off
	v_lshl_add_u64 v[110:111], v[4:5], 0, v[60:61]
	v_lshlrev_b64 v[58:59], 9, v[58:59]
	v_lshlrev_b64 v[64:65], 15, v[62:63]
	v_ashrrev_i32_e32 v67, 31, v66
	v_add_u32_e32 v70, 24, v0
	global_load_dwordx4 v[54:57], v[54:55], off
	v_lshl_add_u64 v[58:59], v[6:7], 0, v[58:59]
	global_load_dwordx2 v[112:113], v[110:111], off
	v_lshl_add_u64 v[114:115], v[4:5], 0, v[64:65]
	v_lshlrev_b64 v[62:63], 9, v[62:63]
	v_lshlrev_b64 v[68:69], 15, v[66:67]
	v_ashrrev_i32_e32 v71, 31, v70
	global_load_dwordx4 v[58:61], v[58:59], off
	v_lshl_add_u64 v[62:63], v[6:7], 0, v[62:63]
	global_load_dwordx2 v[116:117], v[114:115], off
	v_lshl_add_u64 v[118:119], v[4:5], 0, v[68:69]
	v_lshlrev_b64 v[66:67], 9, v[66:67]
	v_lshlrev_b64 v[72:73], 15, v[70:71]
	v_add_u32_e32 v74, 25, v0
	global_load_dwordx4 v[62:65], v[62:63], off
	v_lshl_add_u64 v[66:67], v[6:7], 0, v[66:67]
	global_load_dwordx2 v[120:121], v[118:119], off
	v_lshl_add_u64 v[122:123], v[4:5], 0, v[72:73]
	v_lshlrev_b64 v[70:71], 9, v[70:71]
	v_ashrrev_i32_e32 v75, 31, v74
	global_load_dwordx4 v[66:69], v[66:67], off
	v_lshl_add_u64 v[70:71], v[6:7], 0, v[70:71]
	global_load_dwordx2 v[124:125], v[122:123], off
	v_lshlrev_b64 v[76:77], 15, v[74:75]
	global_load_dwordx4 v[70:73], v[70:71], off
	v_lshl_add_u64 v[126:127], v[4:5], 0, v[76:77]
	v_lshlrev_b64 v[74:75], 9, v[74:75]
	global_load_dwordx2 v[128:129], v[126:127], off
	v_lshl_add_u64 v[74:75], v[6:7], 0, v[74:75]
	global_load_dwordx4 v[74:77], v[74:75], off
	v_cvt_pk_bf16_f32 v8, v8, v9
	v_cvt_pk_bf16_f32 v9, v14, v15
	global_store_dwordx2 v[10:11], v[8:9], off nt
	s_waitcnt vmcnt(26)
	v_lshlrev_b32_e32 v8, 16, v78
	v_and_b32_e32 v9, 0xffff0000, v78
	s_waitcnt vmcnt(25)
	v_pk_fma_f32 v[8:9], v[16:17], v[26:27], v[8:9]
	s_waitcnt vmcnt(24)
	v_lshlrev_b32_e32 v16, 16, v82
	v_and_b32_e32 v17, 0xffff0000, v82
	v_cvt_pk_bf16_f32 v14, v8, v9
	s_waitcnt vmcnt(23)
	v_pk_fma_f32 v[8:9], v[30:31], v[8:9], v[16:17]
	v_lshlrev_b32_e32 v16, 16, v79
	v_and_b32_e32 v17, 0xffff0000, v79
	v_pk_fma_f32 v[16:17], v[18:19], v[28:29], v[16:17]
	s_waitcnt vmcnt(22)
	v_lshlrev_b32_e32 v18, 16, v87
	v_cvt_pk_bf16_f32 v15, v16, v17
	global_store_dwordx2 v[80:81], v[14:15], off nt
	v_lshlrev_b32_e32 v14, 16, v83
	v_and_b32_e32 v15, 0xffff0000, v83
	v_pk_fma_f32 v[14:15], v[32:33], v[16:17], v[14:15]
	v_cvt_pk_bf16_f32 v16, v8, v9
	v_and_b32_e32 v19, 0xffff0000, v87
	v_cvt_pk_bf16_f32 v17, v14, v15
	global_store_dwordx2 v[84:85], v[16:17], off nt
	v_lshlrev_b32_e32 v16, 16, v86
	v_and_b32_e32 v17, 0xffff0000, v86
	s_waitcnt vmcnt(23)
	v_pk_fma_f32 v[8:9], v[34:35], v[8:9], v[16:17]
	s_waitcnt vmcnt(22)
	v_lshlrev_b32_e32 v28, 16, v90
	v_cvt_pk_bf16_f32 v16, v8, v9
	v_and_b32_e32 v29, 0xffff0000, v90
	v_pk_fma_f32 v[14:15], v[36:37], v[14:15], v[18:19]
	s_waitcnt vmcnt(21)
	v_pk_fma_f32 v[8:9], v[38:39], v[8:9], v[28:29]
	v_cvt_pk_bf16_f32 v17, v14, v15
	s_waitcnt vmcnt(20)
	v_lshlrev_b32_e32 v28, 16, v94
	v_and_b32_e32 v29, 0xffff0000, v94
	global_store_dwordx2 v[88:89], v[16:17], off nt
	v_lshlrev_b32_e32 v16, 16, v91
	v_and_b32_e32 v17, 0xffff0000, v91
	s_waitcnt vmcnt(20)
	v_pk_fma_f32 v[28:29], v[42:43], v[8:9], v[28:29]
	v_pk_fma_f32 v[14:15], v[40:41], v[14:15], v[16:17]
	v_cvt_pk_bf16_f32 v8, v8, v9
	s_waitcnt vmcnt(19)
; DI unsigned pk2(float lo, float hi) { unsigned r; asm volatile("v_cvt_pk_bf16_f32 %0, %1, %2" : "=v"(r) : "v"(lo), "v"(hi)); return r; }
; DI float bflo(unsigned u) { return __uint_as_float(u << 16); }
; DI float bfhi(unsigned u) { return __uint_as_float(u & 0xffff0000u); }
; template <int NB> DI void hgrn_b2_steps(const Prm& p, int item, int v, int d4, float (&S)[4]) {
;     ...
;     for (int i = 0; i < NB; ++i) { uu[i] = *(const u32x2*)(p.UT + (size_t)(item + i) * 16384 + v * 128 + d4); al[i] = *(const f32x4*)(p.AL + (size_t)(item + i) * 128 + d4); }
; #pragma unroll
;     for (int i = 0; i < NB; ++i) { u32x2 o; o.x = pk2(S[0], S[1]); o.y = pk2(S[2], S[3]);
;         *(u32x2*)(p.UT + (size_t)(item + i) * 16384 + v * 128 + d4) = o;
;         S[0] = al[i][0] * S[0] + bflo(uu[i].x); S[1] = al[i][1] * S[1] + bfhi(uu[i].x); S[2] = al[i][2] * S[2] + bflo(uu[i].y); S[3] = al[i][3] * S[3] + bfhi(uu[i].y); }
; }
; DI void hgrn_b2(const Prm& p, int gtid, int GT) {
;     for (int idx = gtid; idx < 64 * 4096; idx += GT) {
;         const int bhx = idx >> 12, e = idx & 4095, v = e >> 5, d4 = (e & 31) * 4; const bool smp = bhx >= 32;
;         float S[4] = {0.f, 0.f, 0.f, 0.f};
;         if (smp) {
; #pragma unroll
;             for (int j = 0; j < 4; ++j) S[j] = p.state_hgrn[((size_t)(bhx - 32) * 128 + d4 + j) * 128 + v];
;             hgrn_b2_steps<1>(p, 2080 + (bhx - 32), v, d4, S); }
	v_lshlrev_b32_e32 v30, 16, v98
	v_cvt_pk_bf16_f32 v9, v14, v15
	global_store_dwordx2 v[92:93], v[8:9], off nt
	v_lshlrev_b32_e32 v8, 16, v95
	v_and_b32_e32 v9, 0xffff0000, v95
	v_pk_fma_f32 v[8:9], v[44:45], v[14:15], v[8:9]
	v_cvt_pk_bf16_f32 v14, v28, v29
	v_and_b32_e32 v31, 0xffff0000, v98
	v_cvt_pk_bf16_f32 v15, v8, v9
	global_store_dwordx2 v[96:97], v[14:15], off nt
	v_lshlrev_b32_e32 v14, 16, v99
	v_and_b32_e32 v15, 0xffff0000, v99
	s_waitcnt vmcnt(20)
	v_pk_fma_f32 v[30:31], v[46:47], v[28:29], v[30:31]
	v_pk_fma_f32 v[8:9], v[48:49], v[8:9], v[14:15]
	v_cvt_pk_bf16_f32 v14, v30, v31
	s_waitcnt vmcnt(19)
	v_lshlrev_b32_e32 v32, 16, v102
	v_cvt_pk_bf16_f32 v15, v8, v9
	v_and_b32_e32 v33, 0xffff0000, v102
	global_store_dwordx2 v[100:101], v[14:15], off nt
	v_lshlrev_b32_e32 v14, 16, v103
	v_and_b32_e32 v15, 0xffff0000, v103
	s_waitcnt vmcnt(18)
	v_lshlrev_b32_e32 v26, 16, v108
	v_pk_fma_f32 v[32:33], v[50:51], v[30:31], v[32:33]
	v_and_b32_e32 v27, 0xffff0000, v108
	v_lshlrev_b32_e32 v34, 16, v109
	v_pk_fma_f32 v[14:15], v[52:53], v[8:9], v[14:15]
	v_cvt_pk_bf16_f32 v8, v32, v33
	v_and_b32_e32 v35, 0xffff0000, v109
	v_cvt_pk_bf16_f32 v9, v14, v15
	global_store_dwordx2 v[106:107], v[8:9], off nt
	s_waitcnt vmcnt(17)
	v_lshlrev_b32_e32 v8, 16, v112
	v_and_b32_e32 v9, 0xffff0000, v112
	v_lshlrev_b32_e32 v16, 16, v113
	v_and_b32_e32 v17, 0xffff0000, v113
	v_pk_fma_f32 v[18:19], v[54:55], v[32:33], v[26:27]
	v_pk_fma_f32 v[14:15], v[56:57], v[14:15], v[34:35]
	v_cvt_pk_bf16_f32 v26, v18, v19
	s_waitcnt vmcnt(16)
	v_pk_fma_f32 v[18:19], v[58:59], v[18:19], v[8:9]
	s_waitcnt vmcnt(15)
	v_lshlrev_b32_e32 v8, 16, v116
	v_and_b32_e32 v9, 0xffff0000, v116
	v_pk_fma_f32 v[16:17], v[60:61], v[14:15], v[16:17]
	v_lshlrev_b32_e32 v34, 16, v117
	v_and_b32_e32 v35, 0xffff0000, v117
	v_cvt_pk_bf16_f32 v27, v14, v15
	global_store_dwordx2 v[110:111], v[26:27], off nt
	v_cvt_pk_bf16_f32 v14, v18, v19
	v_cvt_pk_bf16_f32 v15, v16, v17
	s_waitcnt vmcnt(15)
	v_pk_fma_f32 v[28:29], v[62:63], v[18:19], v[8:9]
	s_waitcnt vmcnt(14)
	v_lshlrev_b32_e32 v8, 16, v120
	v_and_b32_e32 v9, 0xffff0000, v120
	v_pk_fma_f32 v[34:35], v[64:65], v[16:17], v[34:35]
	v_lshlrev_b32_e32 v36, 16, v121
	v_and_b32_e32 v37, 0xffff0000, v121
	global_store_dwordx2 v[114:115], v[14:15], off nt
	v_cvt_pk_bf16_f32 v14, v28, v29
	v_cvt_pk_bf16_f32 v15, v34, v35
	s_waitcnt vmcnt(14)
	v_pk_fma_f32 v[30:31], v[66:67], v[28:29], v[8:9]
	s_waitcnt vmcnt(13)
	v_lshlrev_b32_e32 v8, 16, v124
	v_and_b32_e32 v9, 0xffff0000, v124
	v_pk_fma_f32 v[36:37], v[68:69], v[34:35], v[36:37]
	v_lshlrev_b32_e32 v38, 16, v125
	v_and_b32_e32 v39, 0xffff0000, v125
	global_store_dwordx2 v[118:119], v[14:15], off nt
	v_cvt_pk_bf16_f32 v14, v30, v31
	v_cvt_pk_bf16_f32 v15, v36, v37
	s_waitcnt vmcnt(13)
	v_pk_fma_f32 v[32:33], v[70:71], v[30:31], v[8:9]
	v_pk_fma_f32 v[38:39], v[72:73], v[36:37], v[38:39]
	global_store_dwordx2 v[122:123], v[14:15], off nt
	v_cvt_pk_bf16_f32 v14, v32, v33
	v_cvt_pk_bf16_f32 v15, v38, v39
	s_waitcnt vmcnt(13)
	v_lshlrev_b32_e32 v8, 16, v128
	v_and_b32_e32 v9, 0xffff0000, v128
	global_store_dwordx2 v[126:127], v[14:15], off nt
	v_lshlrev_b32_e32 v14, 16, v129
	v_and_b32_e32 v15, 0xffff0000, v129
	s_mov_b64 s[16:17], 0x68000
	s_waitcnt vmcnt(13)
	v_pk_fma_f32 v[8:9], v[74:75], v[32:33], v[8:9]
	v_pk_fma_f32 v[14:15], v[76:77], v[38:39], v[14:15]
	s_add_i32 s15, s15, 13
	v_lshl_add_u64 v[10:11], v[10:11], 0, s[16:17]
	s_mov_b64 s[16:17], 0x1a00
	v_lshl_add_u64 v[12:13], v[12:13], 0, s[16:17]
	s_cmp_lt_u32 s15, 52
	v_mov_b32_e32 v16, v8
	v_mov_b32_e32 v17, v9
	v_mov_b32_e32 v18, v14
	v_mov_b32_e32 v19, v15
	s_cbranch_scc1 .LBB0_847
	v_subrev_u32_e32 v0, 32, v23
	v_mov_b64_e32 v[2:3], v[0:1]
.LBB0_849:
	s_or_saveexec_b64 s[12:13], s[12:13]
	v_mov_b64_e32 v[12:13], 0x2080000
	v_lshlrev_b32_e32 v4, 2, v24
	s_xor_b64 exec, exec, s[12:13]
	s_cbranch_execz .LBB0_844
	v_readlane_b32 s16, v254, 54
	v_subrev_u32_e32 v2, 32, v23
	v_mov_b32_e32 v3, v1
	v_mov_b32_e32 v5, v1
	v_readlane_b32 s20, v254, 58
	v_readlane_b32 s21, v254, 59
	v_lshlrev_b64 v[12:13], 16, v[2:3]
	v_readlane_b32 s17, v254, 55
	v_lshl_add_u64 v[8:9], s[20:21], 0, v[4:5]
	v_readlane_b32 s18, v254, 56
	v_readlane_b32 s19, v254, 57
	v_readlane_b32 s22, v254, 60
	v_readlane_b32 s23, v254, 61
	v_readlane_b32 s24, v254, 62
	v_readlane_b32 s25, v254, 63
	v_readlane_b32 s26, v255, 0
	v_readlane_b32 s27, v255, 1
	v_readlane_b32 s28, v255, 2
	v_readlane_b32 s29, v255, 3
	v_readlane_b32 s30, v255, 4
	v_readlane_b32 s31, v255, 5
	v_lshlrev_b32_e32 v14, 9, v22
	v_mov_b32_e32 v15, v1
	v_lshl_add_u64 v[8:9], v[8:9], 0, v[12:13]
	v_lshl_add_u64 v[8:9], v[8:9], 0, v[14:15]
	v_add_u32_e32 v16, 0x800, v23
	v_mov_b32_e32 v17, v1
	v_readlane_b32 s16, v255, 8
	global_load_dword v12, v[8:9], off
	global_load_dword v13, v[8:9], off offset:512
	global_load_dword v14, v[8:9], off offset:1024
	global_load_dword v15, v[8:9], off offset:1536
	v_lshlrev_b64 v[8:9], 15, v[16:17]
	v_readlane_b32 s17, v255, 9
	v_mov_b32_e32 v7, v1
	v_readlane_b32 s18, v255, 10
	v_lshl_add_u64 v[8:9], s[16:17], 0, v[8:9]
	v_lshl_add_u64 v[8:9], v[8:9], 0, v[0:1]
	v_lshl_add_u64 v[8:9], v[8:9], 0, v[6:7]
	v_readlane_b32 s19, v255, 11
	global_load_dwordx2 v[18:19], v[8:9], off
	v_lshlrev_b64 v[8:9], 9, v[16:17]
	v_lshl_add_u64 v[8:9], s[18:19], 0, v[8:9]
	v_mov_b32_e32 v11, v1
	v_lshl_add_u64 v[8:9], v[8:9], 0, v[10:11]
	global_load_dwordx4 v[8:11], v[8:9], off
	v_lshlrev_b32_e32 v16, 15, v16
	v_lshl_add_u64 v[16:17], s[16:17], 0, v[16:17]
	v_lshl_add_u64 v[16:17], v[16:17], 0, v[0:1]
	v_lshl_add_u64 v[6:7], v[16:17], 0, v[6:7]
	v_readlane_b32 s20, v255, 12
	v_readlane_b32 s21, v255, 13
	v_readlane_b32 s22, v255, 14
	v_readlane_b32 s23, v255, 15
	v_readlane_b32 s24, v255, 16
	v_readlane_b32 s25, v255, 17
	v_readlane_b32 s26, v255, 18
	v_readlane_b32 s27, v255, 19
	v_readlane_b32 s28, v255, 20
	v_readlane_b32 s29, v255, 21
	v_readlane_b32 s30, v255, 22
	v_readlane_b32 s31, v255, 23
	s_waitcnt vmcnt(4)
	v_cvt_pk_bf16_f32 v16, v12, v13
	s_waitcnt vmcnt(2)
	v_cvt_pk_bf16_f32 v17, v14, v15
	global_store_dwordx2 v[6:7], v[16:17], off nt
	s_waitcnt vmcnt(2)
	v_lshlrev_b32_e32 v6, 16, v18
	v_and_b32_e32 v7, 0xffff0000, v18
	v_lshlrev_b32_e32 v16, 16, v19
	v_and_b32_e32 v17, 0xffff0000, v19
	s_waitcnt vmcnt(1)
	v_pk_fma_f32 v[8:9], v[12:13], v[8:9], v[6:7]
	v_pk_fma_f32 v[14:15], v[14:15], v[10:11], v[16:17]
	v_mov_b64_e32 v[12:13], 0x2100000
	s_branch .LBB0_844

; DI unsigned pk2(float lo, float hi) { unsigned r; asm volatile("v_cvt_pk_bf16_f32 %0, %1, %2" : "=v"(r) : "v"(lo), "v"(hi)); return r; }
; DI float bflo(unsigned u) { return __uint_as_float(u << 16); }
; DI float bfhi(unsigned u) { return __uint_as_float(u & 0xffff0000u); }
; template <int NB> DI void hgrn_b2_steps(const Prm& p, int item, int v, int d4, float (&S)[4]) {
;     ...
;     for (int i = 0; i < NB; ++i) { uu[i] = *(const u32x2*)(p.UT + (size_t)(item + i) * 16384 + v * 128 + d4); al[i] = *(const f32x4*)(p.AL + (size_t)(item + i) * 128 + d4); }
; #pragma unroll
;     for (int i = 0; i < NB; ++i) { u32x2 o; o.x = pk2(S[0], S[1]); o.y = pk2(S[2], S[3]);
;         *(u32x2*)(p.UT + (size_t)(item + i) * 16384 + v * 128 + d4) = o;
;         S[0] = al[i][0] * S[0] + bflo(uu[i].x); S[1] = al[i][1] * S[1] + bfhi(uu[i].x); S[2] = al[i][2] * S[2] + bflo(uu[i].y); S[3] = al[i][3] * S[3] + bfhi(uu[i].y); }
; DI void hgrn_b2(const Prm& p, int gtid, int GT) {
;     ...
;         else { for (int c0 = 0; c0 < 65; c0 += 13) hgrn_b2_steps<13>(p, bhx * 65 + c0, v, d4, S); }
.LBB0_884:
	v_add_co_u32_e32 v76, vcc, 0x8000, v68
	v_add_u32_e32 v14, s13, v62
	global_load_dwordx2 v[78:79], v[68:69], off
	v_addc_co_u32_e32 v77, vcc, 0, v69, vcc
	v_add_u32_e32 v52, 15, v14
	global_load_dwordx4 v[4:7], v[70:71], off offset:-512
	global_load_dwordx4 v[0:3], v[70:71], off
	global_load_dwordx2 v[130:131], v[76:77], off
	v_lshlrev_b64 v[8:9], 15, v[52:53]
	v_lshlrev_b64 v[10:11], 9, v[52:53]
	v_add_u32_e32 v52, 16, v14
	v_lshl_add_u64 v[122:123], v[64:65], 0, v[8:9]
	v_lshl_add_u64 v[8:9], v[66:67], 0, v[10:11]
	v_lshlrev_b64 v[10:11], 15, v[52:53]
	v_lshlrev_b64 v[12:13], 9, v[52:53]
	v_add_u32_e32 v52, 17, v14
	global_load_dwordx2 v[128:129], v[122:123], off
	global_load_dwordx4 v[48:51], v[8:9], off
	v_lshl_add_u64 v[106:107], v[64:65], 0, v[10:11]
	v_lshl_add_u64 v[8:9], v[66:67], 0, v[12:13]
	v_lshlrev_b64 v[10:11], 15, v[52:53]
	v_lshlrev_b64 v[12:13], 9, v[52:53]
	v_add_u32_e32 v52, 18, v14
	global_load_dwordx2 v[126:127], v[106:107], off
	global_load_dwordx4 v[44:47], v[8:9], off
	v_lshl_add_u64 v[102:103], v[64:65], 0, v[10:11]
	v_lshl_add_u64 v[8:9], v[66:67], 0, v[12:13]
	v_lshlrev_b64 v[10:11], 15, v[52:53]
	v_lshlrev_b64 v[12:13], 9, v[52:53]
	v_add_u32_e32 v52, 19, v14
	global_load_dwordx2 v[124:125], v[102:103], off
	global_load_dwordx4 v[40:43], v[8:9], off
	v_lshl_add_u64 v[94:95], v[64:65], 0, v[10:11]
	v_lshl_add_u64 v[8:9], v[66:67], 0, v[12:13]
	v_lshlrev_b64 v[10:11], 15, v[52:53]
	v_lshlrev_b64 v[12:13], 9, v[52:53]
	v_add_u32_e32 v52, 20, v14
	global_load_dwordx2 v[120:121], v[94:95], off
	global_load_dwordx4 v[36:39], v[8:9], off
	v_lshl_add_u64 v[100:101], v[64:65], 0, v[10:11]
	v_lshl_add_u64 v[8:9], v[66:67], 0, v[12:13]
	v_lshlrev_b64 v[10:11], 15, v[52:53]
	v_lshlrev_b64 v[12:13], 9, v[52:53]
	v_add_u32_e32 v52, 21, v14
	global_load_dwordx2 v[118:119], v[100:101], off
	global_load_dwordx4 v[32:35], v[8:9], off
	v_lshl_add_u64 v[96:97], v[64:65], 0, v[10:11]
	v_lshl_add_u64 v[8:9], v[66:67], 0, v[12:13]
	v_lshlrev_b64 v[10:11], 15, v[52:53]
	v_lshlrev_b64 v[12:13], 9, v[52:53]
	v_add_u32_e32 v52, 22, v14
	global_load_dwordx2 v[114:115], v[96:97], off
	global_load_dwordx4 v[20:23], v[8:9], off
	v_lshl_add_u64 v[90:91], v[64:65], 0, v[10:11]
	v_lshl_add_u64 v[8:9], v[66:67], 0, v[12:13]
	v_lshlrev_b64 v[10:11], 15, v[52:53]
	v_lshlrev_b64 v[12:13], 9, v[52:53]
	v_add_u32_e32 v52, 23, v14
	global_load_dwordx2 v[116:117], v[90:91], off
	global_load_dwordx4 v[24:27], v[8:9], off
	v_lshl_add_u64 v[84:85], v[64:65], 0, v[10:11]
	v_lshl_add_u64 v[8:9], v[66:67], 0, v[12:13]
	v_lshlrev_b64 v[10:11], 15, v[52:53]
	v_lshlrev_b64 v[12:13], 9, v[52:53]
	v_add_u32_e32 v52, 24, v14
	global_load_dwordx2 v[110:111], v[84:85], off
	global_load_dwordx4 v[28:31], v[8:9], off
	v_lshl_add_u64 v[86:87], v[64:65], 0, v[10:11]
	v_lshl_add_u64 v[8:9], v[66:67], 0, v[12:13]
	v_lshlrev_b64 v[10:11], 15, v[52:53]
	v_lshlrev_b64 v[12:13], 9, v[52:53]
	v_add_u32_e32 v52, 25, v14
	global_load_dwordx2 v[112:113], v[86:87], off
	global_load_dwordx4 v[16:19], v[8:9], off
	v_lshl_add_u64 v[88:89], v[64:65], 0, v[10:11]
	v_lshl_add_u64 v[8:9], v[66:67], 0, v[12:13]
	v_lshlrev_b64 v[10:11], 15, v[52:53]
	v_lshlrev_b64 v[98:99], 9, v[52:53]
	global_load_dwordx2 v[108:109], v[88:89], off
	global_load_dwordx4 v[12:15], v[8:9], off
	v_lshl_add_u64 v[92:93], v[64:65], 0, v[10:11]
	v_lshl_add_u64 v[8:9], v[66:67], 0, v[98:99]
	global_load_dwordx2 v[98:99], v[92:93], off
	s_nop 0
	global_load_dwordx4 v[8:11], v[8:9], off
	v_cvt_pk_bf16_f32 v80, v80, v81
	v_cvt_pk_bf16_f32 v81, v82, v83
	global_store_dwordx2 v[68:69], v[80:81], off nt
	s_add_i32 s13, s13, 13
	s_mov_b64 s[14:15], 0x68000
	v_lshl_add_u64 v[70:71], v[70:71], 0, s[6:7]
	s_cmp_lt_u32 s13, 52
	v_lshl_add_u64 v[68:69], v[68:69], 0, s[14:15]
	s_waitcnt vmcnt(26)
	v_lshlrev_b32_e32 v80, 16, v78
	v_and_b32_e32 v81, 0xffff0000, v78
	v_lshlrev_b32_e32 v78, 16, v79
	v_and_b32_e32 v79, 0xffff0000, v79
	s_waitcnt vmcnt(25)
	v_pk_fma_f32 v[4:5], v[72:73], v[4:5], v[80:81]
	v_pk_fma_f32 v[6:7], v[74:75], v[6:7], v[78:79]
	v_cvt_pk_bf16_f32 v72, v4, v5
	s_waitcnt vmcnt(23)
	v_lshlrev_b32_e32 v74, 16, v130
	v_and_b32_e32 v75, 0xffff0000, v130
	v_cvt_pk_bf16_f32 v73, v6, v7
	v_lshlrev_b32_e32 v78, 16, v131
	v_and_b32_e32 v79, 0xffff0000, v131
	v_pk_fma_f32 v[0:1], v[0:1], v[4:5], v[74:75]
	global_store_dwordx2 v[76:77], v[72:73], off nt
	v_pk_fma_f32 v[2:3], v[2:3], v[6:7], v[78:79]
	v_cvt_pk_bf16_f32 v4, v0, v1
	s_waitcnt vmcnt(23)
	v_lshlrev_b32_e32 v6, 16, v128
	v_cvt_pk_bf16_f32 v5, v2, v3
	v_and_b32_e32 v7, 0xffff0000, v128
	v_lshlrev_b32_e32 v72, 16, v129
	v_and_b32_e32 v73, 0xffff0000, v129
	global_store_dwordx2 v[122:123], v[4:5], off nt
	s_waitcnt vmcnt(23)
	v_pk_fma_f32 v[0:1], v[48:49], v[0:1], v[6:7]
	s_waitcnt vmcnt(22)
	v_lshlrev_b32_e32 v4, 16, v126
	v_and_b32_e32 v5, 0xffff0000, v126
	v_pk_fma_f32 v[2:3], v[50:51], v[2:3], v[72:73]
	v_lshlrev_b32_e32 v6, 16, v127
	v_and_b32_e32 v7, 0xffff0000, v127
	v_cvt_pk_bf16_f32 v48, v0, v1
	s_waitcnt vmcnt(21)
	v_pk_fma_f32 v[0:1], v[44:45], v[0:1], v[4:5]
	s_waitcnt vmcnt(20)
	v_lshlrev_b32_e32 v4, 16, v124
	v_and_b32_e32 v5, 0xffff0000, v124
	v_cvt_pk_bf16_f32 v49, v2, v3
	v_pk_fma_f32 v[2:3], v[46:47], v[2:3], v[6:7]
	v_lshlrev_b32_e32 v6, 16, v125
	v_and_b32_e32 v7, 0xffff0000, v125
	s_waitcnt vmcnt(19)
	v_pk_fma_f32 v[4:5], v[40:41], v[0:1], v[4:5]
	s_waitcnt vmcnt(18)
; DI unsigned pk2(float lo, float hi) { unsigned r; asm volatile("v_cvt_pk_bf16_f32 %0, %1, %2" : "=v"(r) : "v"(lo), "v"(hi)); return r; }
; DI float bflo(unsigned u) { return __uint_as_float(u << 16); }
; DI float bfhi(unsigned u) { return __uint_as_float(u & 0xffff0000u); }
; template <int NB> DI void hgrn_b2_steps(const Prm& p, int item, int v, int d4, float (&S)[4]) {
;     ...
;     for (int i = 0; i < NB; ++i) { u32x2 o; o.x = pk2(S[0], S[1]); o.y = pk2(S[2], S[3]);
;         *(u32x2*)(p.UT + (size_t)(item + i) * 16384 + v * 128 + d4) = o;
;         S[0] = al[i][0] * S[0] + bflo(uu[i].x); S[1] = al[i][1] * S[1] + bfhi(uu[i].x); S[2] = al[i][2] * S[2] + bflo(uu[i].y); S[3] = al[i][3] * S[3] + bfhi(uu[i].y); }
; }
; DI void hgrn_b2(const Prm& p, int gtid, int GT) {
;     for (int idx = gtid; idx < 64 * 4096; idx += GT) {
;         const int bhx = idx >> 12, e = idx & 4095, v = e >> 5, d4 = (e & 31) * 4; const bool smp = bhx >= 32;
;         float S[4] = {0.f, 0.f, 0.f, 0.f};
;         if (smp) {
; #pragma unroll
;             for (int j = 0; j < 4; ++j) S[j] = p.state_hgrn[((size_t)(bhx - 32) * 128 + d4 + j) * 128 + v];
;             hgrn_b2_steps<1>(p, 2080 + (bhx - 32), v, d4, S); }
	v_lshlrev_b32_e32 v40, 16, v120
	v_and_b32_e32 v41, 0xffff0000, v120
	global_store_dwordx2 v[106:107], v[48:49], off nt
	v_cvt_pk_bf16_f32 v0, v0, v1
	v_cvt_pk_bf16_f32 v1, v2, v3
	v_pk_fma_f32 v[2:3], v[42:43], v[2:3], v[6:7]
	v_lshlrev_b32_e32 v6, 16, v121
	v_and_b32_e32 v7, 0xffff0000, v121
	s_waitcnt vmcnt(18)
	v_pk_fma_f32 v[36:37], v[36:37], v[4:5], v[40:41]
	s_waitcnt vmcnt(17)
	v_lshlrev_b32_e32 v40, 16, v118
	v_and_b32_e32 v41, 0xffff0000, v118
	global_store_dwordx2 v[102:103], v[0:1], off nt
	v_cvt_pk_bf16_f32 v0, v4, v5
	v_cvt_pk_bf16_f32 v1, v2, v3
	v_pk_fma_f32 v[2:3], v[38:39], v[2:3], v[6:7]
	v_lshlrev_b32_e32 v4, 16, v119
	v_and_b32_e32 v5, 0xffff0000, v119
	s_waitcnt vmcnt(16)
	v_lshlrev_b32_e32 v6, 16, v114
	v_pk_fma_f32 v[32:33], v[32:33], v[36:37], v[40:41]
	v_and_b32_e32 v7, 0xffff0000, v114
	v_lshlrev_b32_e32 v38, 16, v115
	global_store_dwordx2 v[94:95], v[0:1], off nt
	v_cvt_pk_bf16_f32 v0, v36, v37
	v_cvt_pk_bf16_f32 v1, v2, v3
	v_pk_fma_f32 v[2:3], v[34:35], v[2:3], v[4:5]
	v_and_b32_e32 v39, 0xffff0000, v115
	global_store_dwordx2 v[100:101], v[0:1], off nt
	v_cvt_pk_bf16_f32 v0, v32, v33
	v_cvt_pk_bf16_f32 v1, v2, v3
	s_waitcnt vmcnt(16)
	v_lshlrev_b32_e32 v4, 16, v116
	v_and_b32_e32 v5, 0xffff0000, v116
	v_lshlrev_b32_e32 v34, 16, v117
	v_and_b32_e32 v35, 0xffff0000, v117
	v_pk_fma_f32 v[6:7], v[20:21], v[32:33], v[6:7]
	v_pk_fma_f32 v[2:3], v[22:23], v[2:3], v[38:39]
	global_store_dwordx2 v[96:97], v[0:1], off nt
	v_cvt_pk_bf16_f32 v0, v6, v7
	s_waitcnt vmcnt(16)
	v_pk_fma_f32 v[4:5], v[24:25], v[6:7], v[4:5]
	s_waitcnt vmcnt(15)
	v_lshlrev_b32_e32 v6, 16, v110
	v_and_b32_e32 v7, 0xffff0000, v110
	v_pk_fma_f32 v[20:21], v[26:27], v[2:3], v[34:35]
	v_lshlrev_b32_e32 v22, 16, v111
	v_and_b32_e32 v23, 0xffff0000, v111
	v_cvt_pk_bf16_f32 v1, v2, v3
	s_waitcnt vmcnt(14)
	v_pk_fma_f32 v[2:3], v[28:29], v[4:5], v[6:7]
	s_waitcnt vmcnt(13)
	v_lshlrev_b32_e32 v6, 16, v112
	v_and_b32_e32 v7, 0xffff0000, v112
	v_pk_fma_f32 v[22:23], v[30:31], v[20:21], v[22:23]
	v_lshlrev_b32_e32 v24, 16, v113
	v_and_b32_e32 v25, 0xffff0000, v113
	global_store_dwordx2 v[90:91], v[0:1], off nt
	v_cvt_pk_bf16_f32 v0, v4, v5
	v_cvt_pk_bf16_f32 v1, v20, v21
	s_waitcnt vmcnt(13)
	v_pk_fma_f32 v[4:5], v[16:17], v[2:3], v[6:7]
	s_waitcnt vmcnt(12)
	v_lshlrev_b32_e32 v6, 16, v108
	v_and_b32_e32 v7, 0xffff0000, v108
	v_pk_fma_f32 v[16:17], v[18:19], v[22:23], v[24:25]
	v_lshlrev_b32_e32 v18, 16, v109
	v_and_b32_e32 v19, 0xffff0000, v109
	global_store_dwordx2 v[84:85], v[0:1], off nt
	v_cvt_pk_bf16_f32 v0, v2, v3
	v_cvt_pk_bf16_f32 v1, v22, v23
	s_waitcnt vmcnt(12)
	v_pk_fma_f32 v[2:3], v[12:13], v[4:5], v[6:7]
	s_waitcnt vmcnt(11)
	v_lshlrev_b32_e32 v6, 16, v98
	v_and_b32_e32 v7, 0xffff0000, v98
	v_pk_fma_f32 v[12:13], v[14:15], v[16:17], v[18:19]
	global_store_dwordx2 v[86:87], v[0:1], off nt
	v_cvt_pk_bf16_f32 v0, v4, v5
	v_lshlrev_b32_e32 v4, 16, v99
	v_and_b32_e32 v5, 0xffff0000, v99
	s_waitcnt vmcnt(11)
	v_pk_fma_f32 v[80:81], v[8:9], v[2:3], v[6:7]
	v_pk_fma_f32 v[82:83], v[10:11], v[12:13], v[4:5]
	v_cvt_pk_bf16_f32 v1, v16, v17
	v_mov_b32_e32 v72, v80
	v_mov_b32_e32 v73, v81
	v_mov_b32_e32 v74, v82
	v_mov_b32_e32 v75, v83
	global_store_dwordx2 v[88:89], v[0:1], off nt
	v_cvt_pk_bf16_f32 v0, v2, v3
	v_cvt_pk_bf16_f32 v1, v12, v13
	global_store_dwordx2 v[92:93], v[0:1], off nt
	s_cbranch_scc1 .LBB0_884
	v_mov_b32_e32 v61, v53
	v_lshlrev_b64 v[0:1], 16, v[60:61]
.LBB0_886:
	s_or_saveexec_b64 s[10:11], s[10:11]
	v_mov_b64_e32 v[4:5], 0x2080000
	s_xor_b64 exec, exec, s[10:11]
	s_cbranch_execz .LBB0_881
	v_subrev_u32_e32 v0, 32, v60
	v_mov_b32_e32 v1, v53
	v_lshlrev_b64 v[0:1], 16, v[0:1]
	v_lshlrev_b32_e32 v4, 9, v134
	v_mov_b32_e32 v5, v53
	v_lshl_add_u64 v[6:7], v[58:59], 0, v[0:1]
	v_lshl_add_u64 v[4:5], v[6:7], 0, v[4:5]
	v_add_u32_e32 v10, 0x800, v60
	v_mov_b32_e32 v11, v53
	global_load_dword v6, v[4:5], off
	global_load_dword v7, v[4:5], off offset:512
	global_load_dword v8, v[4:5], off offset:1024
	global_load_dword v9, v[4:5], off offset:1536
	v_lshlrev_b64 v[4:5], 15, v[10:11]
	v_lshl_add_u64 v[4:5], v[54:55], 0, v[4:5]
	v_lshl_add_u64 v[4:5], v[4:5], 0, v[52:53]
	v_readlane_b32 s16, v255, 8
	global_load_dwordx2 v[12:13], v[4:5], off
	v_lshlrev_b32_e32 v4, 9, v10
	v_mov_b32_e32 v5, v53
	v_readlane_b32 s18, v255, 10
	v_readlane_b32 s19, v255, 11
	v_mov_b32_e32 v3, v53
	v_lshlrev_b32_e32 v10, 15, v10
	v_lshl_add_u64 v[4:5], s[18:19], 0, v[4:5]
	v_lshl_add_u64 v[2:3], v[4:5], 0, v[2:3]
	global_load_dwordx4 v[2:5], v[2:3], off
	v_lshl_add_u64 v[10:11], v[54:55], 0, v[10:11]
	v_lshl_add_u64 v[10:11], v[10:11], 0, v[52:53]
	v_readlane_b32 s17, v255, 9
	v_readlane_b32 s20, v255, 12
	v_readlane_b32 s21, v255, 13
	v_readlane_b32 s22, v255, 14
	v_readlane_b32 s23, v255, 15
	v_readlane_b32 s24, v255, 16
	v_readlane_b32 s25, v255, 17
	v_readlane_b32 s26, v255, 18
	v_readlane_b32 s27, v255, 19
	v_readlane_b32 s28, v255, 20
	v_readlane_b32 s29, v255, 21
	v_readlane_b32 s30, v255, 22
	v_readlane_b32 s31, v255, 23
	s_waitcnt vmcnt(4)
	v_cvt_pk_bf16_f32 v14, v6, v7
	s_waitcnt vmcnt(2)
	v_cvt_pk_bf16_f32 v15, v8, v9
	global_store_dwordx2 v[10:11], v[14:15], off nt
	s_waitcnt vmcnt(2)
	v_lshlrev_b32_e32 v16, 16, v12
	v_and_b32_e32 v17, 0xffff0000, v12
	v_lshlrev_b32_e32 v12, 16, v13
	v_and_b32_e32 v13, 0xffff0000, v13
	s_waitcnt vmcnt(1)
	v_pk_fma_f32 v[80:81], v[6:7], v[2:3], v[16:17]
	v_pk_fma_f32 v[82:83], v[8:9], v[4:5], v[12:13]
	v_mov_b64_e32 v[4:5], 0x2100000
	s_branch .LBB0_881

; #define LAS __attribute__((address_space(3)))
; DI unsigned pk2(float lo, float hi) { unsigned r; asm volatile("v_cvt_pk_bf16_f32 %0, %1, %2" : "=v"(r) : "v"(lo), "v"(hi)); return r; }
; #define MFMA16(a, b, c) __builtin_amdgcn_mfma_f32_16x16x32_bf16((a), (b), (c), 0, 0, 0)
; DI f32x2v gelu_pk(f32x2v v) {
;     const f32x2v av = __builtin_elementwise_abs(v), d = av * 0.2316418882f + 1.0f;
;     f32x2v t; t.x = __builtin_amdgcn_rcpf(d.x); t.y = __builtin_amdgcn_rcpf(d.y);
;     f32x2v q = t * 0.5307027145f + (-0.7265760135f); q = q * t + 0.7107068705f; q = q * t + (-0.142248368f); q = q * t + 0.127414796f; q = q * t;
;     const f32x2v s = (v * v) * (-0.72134752044f);
;     f32x2v e; e.x = __builtin_amdgcn_exp2f(s.x); e.y = __builtin_amdgcn_exp2f(s.y);
;     const f32x2v m = v * (q * e), r = v - m;
;     f32x2v o; o.x = v.x < 0.f ? m.x : r.x; o.y = v.y < 0.f ? m.y : r.y; return o;
; DI void s5_d_lds(const Prm& p, LAS unsigned char* lds, int tid, int lane, int wave) {
;     ...
;             for (int t = 0; t < 16; ++t) { f32x4 acc = {0.f, 0.f, 0.f, 0.f};
; #pragma unroll
;                 for (int ks = 0; ks < 8; ++ks) if (ks <= (t >> 1)) {
;                     const int tau = t - 2 * ks - hi;
;                     union { bf16x8 v; u32x4v u; } a; a.v = *(const LAS bf16x8*)(lds + (tau < 0 ? 0 : tau) * 768 + lb);
;                     if (tau < 0) a.u = (u32x4v){0u, 0u, 0u, 0u};
;                     acc = MFMA16(a.v, uf[ks], acc); }
; #pragma unroll
;                 for (int ks = 0; ks < 4; ++ks) { const bf16x8 a = *(const LAS bf16x8*)(lds + 12288 + (t * 16 + fr) * 272 + 64 * ks + 16 * fq); acc = MFMA16(a, xf[ks], acc); }
;                 const f32x2v y0 = gelu_pk((f32x2v){acc[0], acc[1]}), y1 = gelu_pk((f32x2v){acc[2], acc[3]});
;                 u32x2 o; o.x = pk2(y0.x, y0.y); o.y = pk2(y1.x, y1.y);
;                 if (ok) *(u32x2*)(p.YG + ((size_t)(16 * (16 * mt + fr) + t)) * 512 + 16 * g + 4 * fq) = o; }
.LBB0_1116:
	ds_read_b128 v[90:93], v89
	ds_read_b128 v[94:97], v89 offset:64
	s_waitcnt lgkmcnt(1)
	v_mfma_f32_16x16x32_bf16 v[48:51], v[90:93], v[32:35], v[48:51]
	ds_read_b128 v[90:93], v89 offset:128
	s_waitcnt lgkmcnt(1)
	v_mfma_f32_16x16x32_bf16 v[48:51], v[94:97], v[36:39], v[48:51]
	ds_read_b128 v[94:97], v89 offset:192
	s_waitcnt lgkmcnt(1)
	v_mfma_f32_16x16x32_bf16 v[48:51], v[90:93], v[40:43], v[48:51]
	v_mov_b64_e32 v[90:91], s[10:11]
	s_waitcnt lgkmcnt(0)
	v_mfma_f32_16x16x32_bf16 v[48:51], v[94:97], v[44:47], v[48:51]
	s_nop 7
	v_and_b32_e32 v93, 0x7fffffff, v49
	v_and_b32_e32 v92, 0x7fffffff, v48
	v_pk_fma_f32 v[92:93], v[92:93], s[6:7], 1.0 op_sel_hi:[1,0,0]
	v_pk_mul_f32 v[96:97], v[48:49], v[48:49]
	v_rcp_f32_e32 v92, v92
	v_rcp_f32_e32 v93, v93
	v_and_b32_e32 v99, 0x7fffffff, v51
	v_and_b32_e32 v98, 0x7fffffff, v50
	v_pk_mul_f32 v[96:97], v[96:97], s[18:19] op_sel_hi:[1,0]
	v_pk_fma_f32 v[100:101], v[92:93], s[8:9], v[90:91] op_sel_hi:[1,0,0]
	v_pk_fma_f32 v[98:99], v[98:99], s[6:7], 1.0 op_sel_hi:[1,0,0]
	v_exp_f32_e32 v96, v96
	v_exp_f32_e32 v97, v97
	v_pk_fma_f32 v[100:101], v[92:93], v[100:101], s[12:13] op_sel_hi:[1,1,0]
	v_rcp_f32_e32 v98, v98
	v_rcp_f32_e32 v99, v99
	v_pk_fma_f32 v[100:101], v[92:93], v[100:101], s[14:15] op_sel_hi:[1,1,0]
	v_pk_mul_f32 v[94:95], v[50:51], v[50:51]
	v_pk_fma_f32 v[100:101], v[92:93], v[100:101], s[16:17] op_sel_hi:[1,1,0]
	v_pk_mul_f32 v[94:95], v[94:95], s[18:19] op_sel_hi:[1,0]
	v_pk_mul_f32 v[92:93], v[92:93], v[100:101]
	v_pk_fma_f32 v[90:91], v[98:99], s[8:9], v[90:91] op_sel_hi:[1,0,0]
	v_pk_mul_f32 v[92:93], v[96:97], v[92:93]
	v_cmp_gt_f32_e64 s[2:3], 0, v48
	v_pk_mul_f32 v[96:97], v[48:49], v[92:93]
	v_pk_fma_f32 v[92:93], v[48:49], v[92:93], v[48:49] neg_lo:[1,0,0] neg_hi:[1,0,0]
	v_pk_fma_f32 v[90:91], v[98:99], v[90:91], s[12:13] op_sel_hi:[1,1,0]
	v_cndmask_b32_e64 v92, v92, v96, s[2:3]
	v_cmp_gt_f32_e64 s[2:3], 0, v49
	v_exp_f32_e32 v48, v94
	v_exp_f32_e32 v49, v95
	v_pk_fma_f32 v[90:91], v[98:99], v[90:91], s[14:15] op_sel_hi:[1,1,0]
	v_cndmask_b32_e64 v93, v93, v97, s[2:3]
	v_pk_fma_f32 v[90:91], v[98:99], v[90:91], s[16:17] op_sel_hi:[1,1,0]
	v_cmp_gt_f32_e64 s[2:3], 0, v50
	v_pk_mul_f32 v[90:91], v[98:99], v[90:91]
	s_nop 0
	v_pk_mul_f32 v[48:49], v[48:49], v[90:91]
	s_nop 0
	v_pk_mul_f32 v[90:91], v[50:51], v[48:49]
	v_pk_fma_f32 v[48:49], v[50:51], v[48:49], v[50:51] neg_lo:[1,0,0] neg_hi:[1,0,0]
	s_nop 0
	v_cndmask_b32_e64 v50, v48, v90, s[2:3]
	v_cmp_gt_f32_e64 s[2:3], 0, v51
	v_cvt_pk_bf16_f32 v48, v92, v93
	s_nop 1
	v_cndmask_b32_e64 v49, v49, v91, s[2:3]
	v_cvt_pk_bf16_f32 v49, v50, v49
	s_and_saveexec_b64 s[2:3], s[0:1]
	s_cbranch_execz .LBB0_1107
	v_add_u32_e32 v50, s4, v52
	v_ashrrev_i32_e32 v51, 31, v50
	v_lshlrev_b64 v[50:51], 10, v[50:51]
	v_lshl_add_u64 v[50:51], v[70:71], 0, v[50:51]
	global_store_dwordx2 v[50:51], v[48:49], off nt
	s_branch .LBB0_1107

; DI unsigned pk2(float lo, float hi) { unsigned r; asm volatile("v_cvt_pk_bf16_f32 %0, %1, %2" : "=v"(r) : "v"(lo), "v"(hi)); return r; }
; DI unsigned short f2bf(float f) { return (unsigned short)(pk2(f, 0.f) & 0xffffu); }
; DI size_t kf_index(int seqh, int nkt, int key, int d) { return ((((size_t)seqh * nkt + (key >> 5)) * 8 + (d >> 4)) * 64 + ((key & 31) + 32 * ((d >> 3) & 1))) * 8 + (d & 7); }
; DI void cache_convert(const Prm& p, int gtid, int GT) {
;     for (size_t i = (size_t)gtid; i < (size_t)8 * 1024 * 256; i += (size_t)GT) {
;         const size_t row = i >> 8; const int c4 = (int)(i & 255) * 4, b = (int)(row >> 10), pos = (int)(row & 1023), h = c4 >> 7, d = c4 & 127;
;         const f32x4 k = *(const f32x4*)(p.cache_k + row * 1024 + c4); u32x2 o; o.x = pk2(k.x, k.y); o.y = pk2(k.z, k.w);
;         *(u32x2*)(p.KS + kf_index(b * 8 + h, 34, pos, d)) = o;
;         const f32x4 v = *(const f32x4*)(p.cache_v + row * 1024 + c4); bf16_t* vt = p.VTS + vf_index(b * 8 + h, 34, pos, d);
;         vt[0] = f2bf(v.x); vt[8] = f2bf(v.y); vt[16] = f2bf(v.z); vt[24] = f2bf(v.w); }
; }
.LBB0_2041:
	v_alignbit_b32 v5, v3, v2, 8
	v_bfe_u32 v12, v4, 7, 3
	v_lshrrev_b32_e32 v16, 15, v2
	v_and_b32_e32 v14, 0x7c, v4
	v_and_or_b32 v12, v16, 56, v12
	v_bfe_u32 v16, v5, 5, 5
	v_lshrrev_b64 v[6:7], 8, v[2:3]
	v_and_b32_e32 v17, 4, v4
	v_lshlrev_b32_e32 v18, 2, v14
	v_and_b32_e32 v19, 31, v5
	v_mad_u32_u24 v16, v12, 34, v16
	v_and_b32_e32 v0, 0x3fc, v4
	v_lshlrev_b64 v[10:11], 12, v[6:7]
	v_lshlrev_b32_e32 v14, 1, v17
	v_and_b32_e32 v12, 0x1c0, v18
	v_and_or_b32 v17, v18, 32, v19
	v_lshlrev_b32_e32 v18, 9, v16
	v_lshlrev_b32_e32 v0, 2, v0
	v_lshl_add_u64 v[6:7], s[46:47], 0, v[10:11]
	v_mov_b32_e32 v13, v1
	v_or3_b32 v12, v18, v12, v17
	v_lshl_add_u64 v[6:7], v[6:7], 0, v[0:1]
	v_mov_b32_e32 v15, v1
	v_lshl_add_u64 v[12:13], v[12:13], 4, s[14:15]
	global_load_dwordx4 v[6:9], v[6:7], off
	v_lshl_add_u64 v[10:11], s[48:49], 0, v[10:11]
	v_lshl_add_u64 v[12:13], v[12:13], 0, v[14:15]
	v_lshl_add_u64 v[10:11], v[10:11], 0, v[0:1]
	s_waitcnt vmcnt(0)
	v_cvt_pk_bf16_f32 v6, v6, v7
	v_cvt_pk_bf16_f32 v7, v8, v9
	global_store_dwordx2 v[12:13], v[6:7], off nt
	global_load_dwordx4 v[6:9], v[10:11], off
	v_lshrrev_b32_e32 v0, 10, v2
	v_and_b32_e32 v11, 28, v4
	v_lshlrev_b32_e32 v13, 3, v5
	v_bfe_u32 v10, v4, 5, 2
	v_and_b32_e32 v0, 4, v0
	v_and_or_b32 v13, v13, 32, v11
	v_lshlrev_b32_e32 v11, 3, v16
	v_or3_b32 v0, v11, v0, v10
	v_lshlrev_b64 v[10:11], 10, v[0:1]
	v_lshlrev_b32_e32 v0, 4, v13
	v_lshl_add_u64 v[10:11], s[18:19], 0, v[10:11]
	v_lshrrev_b32_e32 v12, 7, v2
	v_lshl_add_u64 v[10:11], v[10:11], 0, v[0:1]
	v_and_b32_e32 v0, 8, v5
	v_lshl_add_u64 v[10:11], v[10:11], 0, v[0:1]
	v_and_b32_e32 v0, 6, v12
	v_lshl_add_u64 v[2:3], v[2:3], 0, s[40:41]
	v_lshl_add_u64 v[10:11], v[10:11], 0, v[0:1]
	s_waitcnt vmcnt(0)
	v_cvt_pk_bf16_f32 v0, v6, v1
	v_cmp_lt_u64_e32 vcc, s[10:11], v[2:3]
	global_store_short v[10:11], v0, off
	v_cvt_pk_bf16_f32 v0, v7, v1
	v_add_u32_e32 v4, s2, v4
	s_or_b64 s[8:9], vcc, s[8:9]
	global_store_short v[10:11], v0, off offset:16
	v_cvt_pk_bf16_f32 v0, v8, v1
	global_store_short v[10:11], v0, off offset:32
	v_cvt_pk_bf16_f32 v0, v9, v1
	global_store_short v[10:11], v0, off offset:48
	s_andn2_b64 exec, exec, s[8:9]
	s_cbranch_execnz .LBB0_2041

; DI unsigned pk2(float lo, float hi) { unsigned r; asm volatile("v_cvt_pk_bf16_f32 %0, %1, %2" : "=v"(r) : "v"(lo), "v"(hi)); return r; }
; DI unsigned short f2bf(float f) { return (unsigned short)(pk2(f, 0.f) & 0xffffu); }
; DI size_t kf_index(int seqh, int nkt, int key, int d) { return ((((size_t)seqh * nkt + (key >> 5)) * 8 + (d >> 4)) * 64 + ((key & 31) + 32 * ((d >> 3) & 1))) * 8 + (d & 7); }
; DI void cache_convert(const Prm& p, int gtid, int GT) {
;     for (size_t i = (size_t)gtid; i < (size_t)8 * 1024 * 256; i += (size_t)GT) {
;         const size_t row = i >> 8; const int c4 = (int)(i & 255) * 4, b = (int)(row >> 10), pos = (int)(row & 1023), h = c4 >> 7, d = c4 & 127;
;         const f32x4 k = *(const f32x4*)(p.cache_k + row * 1024 + c4); u32x2 o; o.x = pk2(k.x, k.y); o.y = pk2(k.z, k.w);
;         *(u32x2*)(p.KS + kf_index(b * 8 + h, 34, pos, d)) = o;
;         const f32x4 v = *(const f32x4*)(p.cache_v + row * 1024 + c4); bf16_t* vt = p.VTS + vf_index(b * 8 + h, 34, pos, d);
;         vt[0] = f2bf(v.x); vt[8] = f2bf(v.y); vt[16] = f2bf(v.z); vt[24] = f2bf(v.w); }
; }
.Lcc_nopf:
	s_mov_b64 exec, s[6:7]
	v_alignbit_b32 v5, v3, v2, 8
	v_bfe_u32 v12, v4, 7, 3
	v_lshrrev_b32_e32 v16, 15, v2
	v_and_b32_e32 v14, 0x7c, v4
	v_and_or_b32 v12, v16, 56, v12
	v_bfe_u32 v16, v5, 5, 5
	v_and_b32_e32 v17, 4, v4
	v_lshlrev_b32_e32 v18, 2, v14
	v_and_b32_e32 v19, 31, v5
	v_mad_u32_u24 v16, v12, 34, v16
	v_lshlrev_b32_e32 v14, 1, v17
	v_and_b32_e32 v12, 0x1c0, v18
	v_and_or_b32 v17, v18, 32, v19
	v_lshlrev_b32_e32 v18, 9, v16
	v_mov_b32_e32 v13, v1
	v_or3_b32 v12, v18, v12, v17
	v_mov_b32_e32 v15, v1
	v_lshl_add_u64 v[12:13], v[12:13], 4, s[14:15]
	v_lshl_add_u64 v[12:13], v[12:13], 0, v[14:15]
	global_store_dwordx2 v[12:13], v[32:33], off nt
	v_lshrrev_b32_e32 v0, 10, v2
	v_and_b32_e32 v11, 28, v4
	v_lshlrev_b32_e32 v13, 3, v5
	v_bfe_u32 v10, v4, 5, 2
	v_and_b32_e32 v0, 4, v0
	v_and_or_b32 v13, v13, 32, v11
	v_lshlrev_b32_e32 v11, 3, v16
	v_or3_b32 v0, v11, v0, v10
	v_lshlrev_b64 v[10:11], 10, v[0:1]
	v_lshlrev_b32_e32 v0, 4, v13
	v_lshl_add_u64 v[10:11], s[18:19], 0, v[10:11]
	v_lshrrev_b32_e32 v12, 7, v2
	v_lshl_add_u64 v[10:11], v[10:11], 0, v[0:1]
	v_and_b32_e32 v0, 8, v5
	v_lshl_add_u64 v[10:11], v[10:11], 0, v[0:1]
	v_and_b32_e32 v0, 6, v12
	v_lshl_add_u64 v[10:11], v[10:11], 0, v[0:1]
	global_store_short v[10:11], v34, off
	global_store_short v[10:11], v35, off offset:16
	global_store_short v[10:11], v36, off offset:32
	global_store_short v[10:11], v37, off offset:48
	v_mov_b32_e32 v2, v38
	v_mov_b32_e32 v3, v39
	v_add_u32_e32 v4, s2, v4
	s_waitcnt vmcnt(5)
	s_andn2_b64 exec, exec, s[10:11]
	s_cbranch_execnz .Lcc_loop
